# phase 5 epilogue: o-gate and mh_w loads of each column step issued together with one wait (were issued and waited one after the other)
# speedup vs baseline: 1.0068x; 1.0068x over previous
.LBB0_506:
	s_or_b32 s33, s91, s81
	v_cndmask_b32_e64 v0, 0, 1, s[0:1]
	s_ashr_i32 s1, s33, 31
	s_add_u32 s0, s88, s33
	s_addc_u32 s1, s89, s1
	s_lshl_b64 s[2:3], s[0:1], 10
	s_add_u32 s56, s85, s2
	s_addc_u32 s57, s90, s3
	v_or_b32_e32 v8, s33, v201
	v_cmp_ne_u32_e32 vcc, 1, v0
	v_lshl_add_u64 v[0:1], s[56:57], 0, v[46:47]
	v_lshlrev_b32_e32 v220, 2, v8
	global_load_dwordx4 v[4:7], v[0:1], off
	s_nop 0
	global_load_dwordx4 v[0:3], v[0:1], off offset:64
	ds_read_b32 v9, v220 offset:2048
	v_sub_u32_e32 v29, v8, v202
	global_load_dwordx4 v[12:15], v[68:69], off
	global_load_dwordx4 v[16:19], v[70:71], off
	global_load_dwordx4 v[188:191], v[56:57], off offset:64
	s_waitcnt lgkmcnt(0)
	v_max_f32_e32 v9, v9, v9
	v_max_f32_e32 v221, v219, v9
	v_sub_f32_e32 v9, v216, v221
	v_mul_f32_e32 v28, 0x3fb8aa3b, v9
	global_load_dwordx4 v[8:11], v[56:57], off
	global_load_dwordx4 v[184:187], v[80:81], off
	global_load_dwordx4 v[20:23], v[72:73], off
	global_load_dwordx4 v[24:27], v[74:75], off
	global_load_dwordx4 v[30:33], v[76:77], off
	global_load_dwordx4 v[180:183], v[78:79], off
	s_mul_i32 s2, s1, 0x1900
	s_mul_hi_u32 s3, s0, 0x1900
	s_add_i32 s3, s3, s2
	s_mul_i32 s2, s0, 0x1900
	s_add_u32 s2, s94, s2
	s_addc_u32 s3, s95, s3
	s_add_u32 s2, s2, s72
	s_addc_u32 s3, s3, 0
	s_lshl_b64 s[22:23], s[0:1], 11
	v_cmp_lt_i32_e64 s[0:1], -1, v29
	v_or_b32_e32 v48, s91, v201
	v_exp_f32_e32 v198, v28
	v_lshl_add_u64 v[238:239], s[56:57], 0, v[38:39]
	s_mov_b32 s91, 16
	s_and_b64 vcc, exec, vcc
	s_waitcnt vmcnt(8)
	v_mfma_f32_16x16x32_bf16 v[12:15], v[12:15], v[4:7], 0
	s_waitcnt vmcnt(5)
	v_mfma_f32_16x16x32_bf16 v[8:11], v[8:11], v[4:7], 0
	v_mfma_f32_16x16x32_bf16 v[188:191], v[188:191], v[0:3], v[8:11]
	s_nop 6
	global_load_dwordx4 v[8:11], v[82:83], off
	v_mfma_f32_16x16x32_bf16 v[16:19], v[16:19], v[4:7], 0
	s_waitcnt vmcnt(4)
	v_mfma_f32_16x16x32_bf16 v[20:23], v[20:23], v[4:7], 0
	s_waitcnt vmcnt(3)
	v_mfma_f32_16x16x32_bf16 v[24:27], v[24:27], v[4:7], 0
	s_waitcnt vmcnt(2)
	v_mfma_f32_16x16x32_bf16 v[30:33], v[30:33], v[4:7], 0
	s_waitcnt vmcnt(1)
	v_mfma_f32_16x16x32_bf16 v[180:183], v[180:183], v[4:7], 0
	v_mfma_f32_16x16x32_bf16 v[184:187], v[184:187], v[4:7], 0
	s_waitcnt vmcnt(0)
	v_mfma_f32_16x16x32_bf16 v[192:195], v[8:11], v[0:3], v[12:15]
	global_load_dwordx4 v[8:11], v[84:85], off
	s_waitcnt vmcnt(0)
	v_mfma_f32_16x16x32_bf16 v[222:225], v[8:11], v[0:3], v[16:19]
	global_load_dwordx4 v[8:11], v[86:87], off
	s_waitcnt vmcnt(0)
	v_mfma_f32_16x16x32_bf16 v[226:229], v[8:11], v[0:3], v[20:23]
	global_load_dwordx4 v[8:11], v[88:89], off
	s_waitcnt vmcnt(0)
	v_mfma_f32_16x16x32_bf16 v[20:23], v[8:11], v[0:3], v[24:27]
	global_load_dwordx4 v[8:11], v[90:91], off
	s_nop 1
	ds_read_b128 v[24:27], v36 offset:1536
	s_waitcnt lgkmcnt(0)
	v_sub_f32_e32 v24, v24, v221
	v_mul_f32_e32 v24, 0x3fb8aa3b, v24
	v_sub_f32_e32 v25, v25, v221
	v_cndmask_b32_e64 v24, v37, v24, s[0:1]
	v_mul_f32_e32 v25, 0x3fb8aa3b, v25
	v_cmp_lt_i32_e64 s[0:1], 0, v29
	v_sub_f32_e32 v26, v26, v221
	v_mul_f32_e32 v26, 0x3fb8aa3b, v26
	v_cndmask_b32_e64 v25, v37, v25, s[0:1]
	v_cmp_lt_i32_e64 s[0:1], 1, v29
	v_sub_f32_e32 v27, v27, v221
	v_mul_f32_e32 v27, 0x3fb8aa3b, v27
	v_cndmask_b32_e64 v26, v37, v26, s[0:1]
	v_cmp_lt_i32_e64 s[0:1], 2, v29
	v_exp_f32_e32 v24, v24
	v_exp_f32_e32 v25, v25
	v_cndmask_b32_e64 v27, v37, v27, s[0:1]
	v_exp_f32_e32 v26, v26
	v_exp_f32_e32 v27, v27
	v_pk_mul_f32 v[24:25], v[188:189], v[24:25]
	v_cmp_lt_i32_e64 s[0:1], 15, v29
	s_waitcnt vmcnt(0)
	v_mfma_f32_16x16x32_bf16 v[16:19], v[8:11], v[0:3], v[30:33]
	global_load_dwordx4 v[8:11], v[92:93], off
	s_nop 1
	v_add_f32_e32 v31, 0, v24
	v_pk_mul_f32 v[26:27], v[190:191], v[26:27]
	v_mad_u32_u24 v30, v48, s86, v204
	v_add_f32_e32 v31, v25, v31
	v_cvt_pk_bf16_f32 v24, v24, v25
	v_cvt_pk_bf16_f32 v25, v26, v27
	v_add_f32_e32 v31, v26, v31
	ds_write_b64 v30, v[24:25] offset:4096
	v_add_f32_e32 v31, v27, v31
	ds_read_b128 v[24:27], v36 offset:1600
	v_mad_u32_u24 v48, v48, s86, v205
	s_waitcnt vmcnt(0)
	v_mfma_f32_16x16x32_bf16 v[12:15], v[8:11], v[0:3], v[180:183]
	global_load_dwordx4 v[8:11], v[94:95], off
	s_waitcnt lgkmcnt(0)
	v_sub_f32_e32 v24, v24, v221
	v_mul_f32_e32 v24, 0x3fb8aa3b, v24
	v_sub_f32_e32 v25, v25, v221
	v_cndmask_b32_e64 v24, v37, v24, s[0:1]
	v_mul_f32_e32 v25, 0x3fb8aa3b, v25
	v_cmp_lt_i32_e64 s[0:1], 16, v29
	v_sub_f32_e32 v26, v26, v221
	v_mul_f32_e32 v26, 0x3fb8aa3b, v26
	v_cndmask_b32_e64 v25, v37, v25, s[0:1]
	v_cmp_lt_i32_e64 s[0:1], 17, v29
	v_sub_f32_e32 v27, v27, v221
	v_mul_f32_e32 v27, 0x3fb8aa3b, v27
	v_cndmask_b32_e64 v26, v37, v26, s[0:1]
	v_cmp_lt_i32_e64 s[0:1], 18, v29
	v_exp_f32_e32 v24, v24
	v_exp_f32_e32 v25, v25
	v_cndmask_b32_e64 v27, v37, v27, s[0:1]
	v_exp_f32_e32 v26, v26
	v_exp_f32_e32 v27, v27
	v_pk_mul_f32 v[24:25], v[192:193], v[24:25]
	v_cmp_lt_i32_e64 s[0:1], 31, v29
	v_add_f32_e32 v31, v24, v31
	v_pk_mul_f32 v[26:27], v[194:195], v[26:27]
	v_add_f32_e32 v31, v25, v31
	v_cvt_pk_bf16_f32 v24, v24, v25
	v_cvt_pk_bf16_f32 v25, v26, v27
	v_add_f32_e32 v31, v26, v31
	ds_write_b64 v30, v[24:25] offset:4128
	v_add_f32_e32 v31, v27, v31
	ds_read_b128 v[24:27], v36 offset:1664
	s_waitcnt vmcnt(0)
	v_mfma_f32_16x16x32_bf16 v[8:11], v[8:11], v[0:3], v[184:187]
	s_waitcnt lgkmcnt(0)
	v_sub_f32_e32 v24, v24, v221
	v_mul_f32_e32 v24, 0x3fb8aa3b, v24
	v_sub_f32_e32 v25, v25, v221
	v_cndmask_b32_e64 v24, v37, v24, s[0:1]
	v_mul_f32_e32 v25, 0x3fb8aa3b, v25
	v_cmp_lt_i32_e64 s[0:1], 32, v29
	v_sub_f32_e32 v26, v26, v221
	v_mul_f32_e32 v26, 0x3fb8aa3b, v26
	v_cndmask_b32_e64 v25, v37, v25, s[0:1]
	v_cmp_lt_i32_e64 s[0:1], 33, v29
	v_sub_f32_e32 v27, v27, v221
	v_mul_f32_e32 v27, 0x3fb8aa3b, v27
	v_cndmask_b32_e64 v26, v37, v26, s[0:1]
	v_cmp_lt_i32_e64 s[0:1], 34, v29
	v_exp_f32_e32 v24, v24
	v_exp_f32_e32 v25, v25
	v_cndmask_b32_e64 v27, v37, v27, s[0:1]
	v_exp_f32_e32 v26, v26
	v_exp_f32_e32 v27, v27
	v_pk_mul_f32 v[24:25], v[222:223], v[24:25]
	v_cmp_lt_i32_e64 s[0:1], 47, v29
	v_add_f32_e32 v31, v24, v31
	v_pk_mul_f32 v[26:27], v[224:225], v[26:27]
	v_add_f32_e32 v31, v25, v31
	v_cvt_pk_bf16_f32 v24, v24, v25
	v_cvt_pk_bf16_f32 v25, v26, v27
	v_add_f32_e32 v31, v26, v31
	ds_write_b64 v30, v[24:25] offset:4160
	v_add_f32_e32 v31, v27, v31
	ds_read_b128 v[24:27], v36 offset:1728
	s_waitcnt lgkmcnt(0)
	v_sub_f32_e32 v24, v24, v221
	v_mul_f32_e32 v24, 0x3fb8aa3b, v24
	v_sub_f32_e32 v25, v25, v221
	v_cndmask_b32_e64 v24, v37, v24, s[0:1]
	v_mul_f32_e32 v25, 0x3fb8aa3b, v25
	v_cmp_lt_i32_e64 s[0:1], 48, v29
	v_sub_f32_e32 v26, v26, v221
	v_mul_f32_e32 v26, 0x3fb8aa3b, v26
	v_cndmask_b32_e64 v25, v37, v25, s[0:1]
	v_cmp_lt_i32_e64 s[0:1], 49, v29
	v_sub_f32_e32 v27, v27, v221
	v_mul_f32_e32 v27, 0x3fb8aa3b, v27
	v_cndmask_b32_e64 v26, v37, v26, s[0:1]
	v_cmp_lt_i32_e64 s[0:1], 50, v29
	v_exp_f32_e32 v24, v24
	v_exp_f32_e32 v25, v25
	v_cndmask_b32_e64 v27, v37, v27, s[0:1]
	v_exp_f32_e32 v26, v26
	v_exp_f32_e32 v27, v27
	v_pk_mul_f32 v[24:25], v[226:227], v[24:25]
	v_cmp_lt_i32_e64 s[0:1], 63, v29
	v_add_f32_e32 v31, v24, v31
	v_pk_mul_f32 v[26:27], v[228:229], v[26:27]
	v_add_f32_e32 v31, v25, v31
	v_cvt_pk_bf16_f32 v24, v24, v25
	v_cvt_pk_bf16_f32 v25, v26, v27
	v_add_f32_e32 v31, v26, v31
	ds_write_b64 v30, v[24:25] offset:4192
	v_add_f32_e32 v180, v27, v31
	ds_read_b128 v[24:27], v36 offset:1792
	s_waitcnt lgkmcnt(0)
	v_sub_f32_e32 v24, v24, v221
	v_mul_f32_e32 v24, 0x3fb8aa3b, v24
	v_sub_f32_e32 v25, v25, v221
	v_cndmask_b32_e64 v24, v37, v24, s[0:1]
	v_mul_f32_e32 v25, 0x3fb8aa3b, v25
	v_cmp_lt_i32_e64 s[0:1], 64, v29
	v_exp_f32_e32 v24, v24
	s_nop 0
	v_cndmask_b32_e64 v25, v37, v25, s[0:1]
	v_exp_f32_e32 v25, v25
	s_movk_i32 s0, 0x41
	v_cmp_lt_i32_e64 s[0:1], s0, v29
	v_pk_mul_f32 v[182:183], v[20:21], v[24:25]
	v_sub_f32_e32 v20, v26, v221
	v_mul_f32_e32 v20, 0x3fb8aa3b, v20
	v_cndmask_b32_e64 v20, v37, v20, s[0:1]
	v_sub_f32_e32 v21, v27, v221
	s_movk_i32 s0, 0x42
	v_mul_f32_e32 v21, 0x3fb8aa3b, v21
	v_cmp_lt_i32_e64 s[0:1], s0, v29
	v_exp_f32_e32 v20, v20
	s_nop 0
	v_cndmask_b32_e64 v21, v37, v21, s[0:1]
	v_exp_f32_e32 v21, v21
	s_movk_i32 s0, 0x4f
	v_cmp_lt_i32_e64 s[0:1], s0, v29
	v_pk_mul_f32 v[184:185], v[22:23], v[20:21]
	v_cvt_pk_bf16_f32 v20, v182, v183
	v_cvt_pk_bf16_f32 v21, v184, v185
	ds_write_b64 v30, v[20:21] offset:4224
	ds_read_b128 v[20:23], v36 offset:1856
	v_mov_b32_e32 v240, v184
	s_waitcnt lgkmcnt(0)
	v_sub_f32_e32 v20, v20, v221
	v_mul_f32_e32 v20, 0x3fb8aa3b, v20
	v_cndmask_b32_e64 v20, v37, v20, s[0:1]
	v_sub_f32_e32 v21, v21, v221
	s_movk_i32 s0, 0x50
	v_mul_f32_e32 v21, 0x3fb8aa3b, v21
	v_cmp_lt_i32_e64 s[0:1], s0, v29
	v_exp_f32_e32 v20, v20
	s_nop 0
	v_cndmask_b32_e64 v21, v37, v21, s[0:1]
	v_exp_f32_e32 v21, v21
	s_movk_i32 s0, 0x51
	v_cmp_lt_i32_e64 s[0:1], s0, v29
	v_pk_mul_f32 v[186:187], v[16:17], v[20:21]
	v_sub_f32_e32 v16, v22, v221
	v_mul_f32_e32 v16, 0x3fb8aa3b, v16
	v_cndmask_b32_e64 v16, v37, v16, s[0:1]
	v_sub_f32_e32 v17, v23, v221
	s_movk_i32 s0, 0x52
	v_mul_f32_e32 v17, 0x3fb8aa3b, v17
	v_cmp_lt_i32_e64 s[0:1], s0, v29
	v_exp_f32_e32 v16, v16
	s_nop 0
	v_cndmask_b32_e64 v17, v37, v17, s[0:1]
	v_exp_f32_e32 v17, v17
	s_movk_i32 s0, 0x5f
	v_cmp_lt_i32_e64 s[0:1], s0, v29
	v_pk_mul_f32 v[188:189], v[18:19], v[16:17]
	v_cvt_pk_bf16_f32 v16, v186, v187
	v_cvt_pk_bf16_f32 v17, v188, v189
	ds_write_b64 v30, v[16:17] offset:4256
	ds_read_b128 v[16:19], v36 offset:1920
	v_mov_b32_e32 v184, v189
	s_waitcnt lgkmcnt(0)
	v_sub_f32_e32 v16, v16, v221
	v_mul_f32_e32 v16, 0x3fb8aa3b, v16
	v_cndmask_b32_e64 v16, v37, v16, s[0:1]
	v_sub_f32_e32 v17, v17, v221
	s_movk_i32 s0, 0x60
	v_mul_f32_e32 v17, 0x3fb8aa3b, v17
	v_cmp_lt_i32_e64 s[0:1], s0, v29
	v_exp_f32_e32 v16, v16
	s_nop 0
	v_cndmask_b32_e64 v17, v37, v17, s[0:1]
	v_exp_f32_e32 v17, v17
	s_movk_i32 s0, 0x61
	v_cmp_lt_i32_e64 s[0:1], s0, v29
	v_pk_mul_f32 v[190:191], v[12:13], v[16:17]
	v_sub_f32_e32 v12, v18, v221
	v_mul_f32_e32 v12, 0x3fb8aa3b, v12
	v_cndmask_b32_e64 v12, v37, v12, s[0:1]
	v_sub_f32_e32 v13, v19, v221
	s_movk_i32 s0, 0x62
	v_mul_f32_e32 v13, 0x3fb8aa3b, v13
	v_cmp_lt_i32_e64 s[0:1], s0, v29
	v_exp_f32_e32 v12, v12
	s_nop 0
	v_cndmask_b32_e64 v13, v37, v13, s[0:1]
	v_exp_f32_e32 v13, v13
	s_movk_i32 s0, 0x6f
	v_cmp_lt_i32_e64 s[0:1], s0, v29
	v_pk_mul_f32 v[192:193], v[14:15], v[12:13]
	v_cvt_pk_bf16_f32 v12, v190, v191
	v_cvt_pk_bf16_f32 v13, v192, v193
	ds_write_b64 v30, v[12:13] offset:4288
	ds_read_b128 v[12:15], v36 offset:1984
	s_waitcnt lgkmcnt(0)
	v_sub_f32_e32 v12, v12, v221
	v_mul_f32_e32 v12, 0x3fb8aa3b, v12
	v_cndmask_b32_e64 v12, v37, v12, s[0:1]
	v_sub_f32_e32 v13, v13, v221
	s_movk_i32 s0, 0x70
	v_mul_f32_e32 v13, 0x3fb8aa3b, v13
	v_cmp_lt_i32_e64 s[0:1], s0, v29
	v_exp_f32_e32 v12, v12
	s_nop 0
	v_cndmask_b32_e64 v13, v37, v13, s[0:1]
	v_exp_f32_e32 v13, v13
	s_movk_i32 s0, 0x71
	v_cmp_lt_i32_e64 s[0:1], s0, v29
	v_pk_mul_f32 v[194:195], v[8:9], v[12:13]
	v_sub_f32_e32 v8, v14, v221
	v_mul_f32_e32 v8, 0x3fb8aa3b, v8
	v_cndmask_b32_e64 v8, v37, v8, s[0:1]
	v_sub_f32_e32 v9, v15, v221
	s_movk_i32 s0, 0x72
	v_mul_f32_e32 v9, 0x3fb8aa3b, v9
	v_cmp_lt_i32_e64 s[0:1], s0, v29
	v_exp_f32_e32 v8, v8
	s_nop 0
	v_cndmask_b32_e64 v9, v37, v9, s[0:1]
	v_exp_f32_e32 v9, v9
	s_nop 0
	v_pk_mul_f32 v[196:197], v[10:11], v[8:9]
	v_cvt_pk_bf16_f32 v8, v194, v195
	v_cvt_pk_bf16_f32 v9, v196, v197
	ds_write_b64 v30, v[8:9] offset:4320
	s_waitcnt lgkmcnt(0)
	s_barrier
	global_load_dwordx4 v[8:11], v[62:63], off offset:16
	global_load_dwordx4 v[12:15], v[62:63], off
	s_waitcnt vmcnt(1)
	v_cvt_pk_bf16_f32 v9, v9, v10
	s_waitcnt vmcnt(0)
	v_cvt_pk_bf16_f32 v12, v12, s0
	v_cvt_pk_bf16_f32 v13, v13, v14
	v_cvt_pk_bf16_f32 v8, v15, v8
	v_perm_b32 v12, v13, v12, s87
	v_alignbit_b32 v13, v8, v13, 16
	v_alignbit_b32 v14, v9, v8, 16
	v_cvt_pk_bf16_f32 v8, v11, s0
	v_alignbit_b32 v15, v8, v9, 16
	s_nop 1
	v_mfma_f32_16x16x32_bf16 v[32:35], v[12:15], v[4:7], 0
	global_load_dwordx4 v[8:11], v[96:97], off offset:16
	global_load_dwordx4 v[12:15], v[96:97], off
	s_waitcnt vmcnt(1)
	v_cvt_pk_bf16_f32 v9, v9, v10
	s_waitcnt vmcnt(0)
	v_cvt_pk_bf16_f32 v12, v12, s0
	v_cvt_pk_bf16_f32 v13, v13, v14
	v_cvt_pk_bf16_f32 v8, v15, v8
	v_perm_b32 v12, v13, v12, s87
	v_alignbit_b32 v13, v8, v13, 16
	v_alignbit_b32 v14, v9, v8, 16
	v_cvt_pk_bf16_f32 v8, v11, s0
	v_alignbit_b32 v15, v8, v9, 16
	s_nop 1
	v_mfma_f32_16x16x32_bf16 v[28:31], v[12:15], v[4:7], 0
	global_load_dwordx4 v[8:11], v[98:99], off offset:16
	global_load_dwordx4 v[12:15], v[98:99], off
	s_waitcnt vmcnt(1)
	v_cvt_pk_bf16_f32 v9, v9, v10
	s_waitcnt vmcnt(0)
	v_cvt_pk_bf16_f32 v12, v12, s0
	v_cvt_pk_bf16_f32 v13, v13, v14
	v_cvt_pk_bf16_f32 v8, v15, v8
	v_perm_b32 v12, v13, v12, s87
	v_alignbit_b32 v13, v8, v13, 16
	v_alignbit_b32 v14, v9, v8, 16
	v_cvt_pk_bf16_f32 v8, v11, s0
	v_alignbit_b32 v15, v8, v9, 16
	s_nop 1
	v_mfma_f32_16x16x32_bf16 v[24:27], v[12:15], v[4:7], 0
	global_load_dwordx4 v[8:11], v[100:101], off offset:16
	global_load_dwordx4 v[12:15], v[100:101], off
	s_waitcnt vmcnt(1)
	v_cvt_pk_bf16_f32 v9, v9, v10
	s_waitcnt vmcnt(0)
	v_cvt_pk_bf16_f32 v12, v12, s0
	v_cvt_pk_bf16_f32 v13, v13, v14
	v_cvt_pk_bf16_f32 v8, v15, v8
	v_perm_b32 v12, v13, v12, s87
	v_alignbit_b32 v13, v8, v13, 16
	v_alignbit_b32 v14, v9, v8, 16
	v_cvt_pk_bf16_f32 v8, v11, s0
	v_alignbit_b32 v15, v8, v9, 16
	s_nop 1
	v_mfma_f32_16x16x32_bf16 v[8:11], v[12:15], v[4:7], 0
	global_load_dwordx4 v[12:15], v[102:103], off offset:16
	global_load_dwordx4 v[16:19], v[102:103], off
	s_waitcnt vmcnt(1)
	v_cvt_pk_bf16_f32 v13, v13, v14
	s_waitcnt vmcnt(0)
	v_cvt_pk_bf16_f32 v16, v16, s0
	v_cvt_pk_bf16_f32 v17, v17, v18
	v_cvt_pk_bf16_f32 v12, v19, v12
	v_perm_b32 v16, v17, v16, s87
	v_alignbit_b32 v17, v12, v17, 16
	v_alignbit_b32 v18, v13, v12, 16
	v_cvt_pk_bf16_f32 v12, v15, s0
	v_alignbit_b32 v19, v12, v13, 16
	s_nop 1
	v_mfma_f32_16x16x32_bf16 v[12:15], v[16:19], v[4:7], 0
	global_load_dwordx4 v[16:19], v[104:105], off offset:16
	global_load_dwordx4 v[20:23], v[104:105], off
	s_waitcnt vmcnt(1)
	v_cvt_pk_bf16_f32 v17, v17, v18
	s_waitcnt vmcnt(0)
	v_cvt_pk_bf16_f32 v20, v20, s0
	v_cvt_pk_bf16_f32 v21, v21, v22
	v_cvt_pk_bf16_f32 v16, v23, v16
	v_perm_b32 v20, v21, v20, s87
	v_alignbit_b32 v21, v16, v21, 16
	v_alignbit_b32 v22, v17, v16, 16
	v_cvt_pk_bf16_f32 v16, v19, s0
	v_alignbit_b32 v23, v16, v17, 16
	s_nop 1
	v_mfma_f32_16x16x32_bf16 v[16:19], v[20:23], v[4:7], 0
	global_load_dwordx4 v[20:23], v[106:107], off offset:16
	global_load_dwordx4 v[222:225], v[106:107], off
	s_waitcnt vmcnt(1)
	v_cvt_pk_bf16_f32 v21, v21, v22
	s_waitcnt vmcnt(0)
	v_cvt_pk_bf16_f32 v181, v222, s0
	v_cvt_pk_bf16_f32 v223, v223, v224
	v_cvt_pk_bf16_f32 v20, v225, v20
	v_perm_b32 v222, v223, v181, s87
	v_alignbit_b32 v223, v20, v223, 16
	v_alignbit_b32 v224, v21, v20, 16
	v_cvt_pk_bf16_f32 v20, v23, s0
	v_alignbit_b32 v225, v20, v21, 16
	s_nop 1
	v_mfma_f32_16x16x32_bf16 v[20:23], v[222:225], v[4:7], 0
	global_load_dwordx4 v[222:225], v[108:109], off offset:16
	global_load_dwordx4 v[226:229], v[108:109], off
	s_waitcnt vmcnt(0)
	v_cvt_pk_bf16_f32 v181, v226, s0
	v_cvt_pk_bf16_f32 v227, v227, v228
	v_perm_b32 v226, v227, v181, s87
	v_cvt_pk_bf16_f32 v181, v229, v222
	v_cvt_pk_bf16_f32 v222, v223, v224
	v_alignbit_b32 v227, v181, v227, 16
	v_alignbit_b32 v228, v222, v181, 16
	v_cvt_pk_bf16_f32 v181, v225, s0
	v_alignbit_b32 v229, v181, v222, 16
	s_nop 1
	v_mfma_f32_16x16x32_bf16 v[4:7], v[226:229], v[4:7], 0
	global_load_dwordx4 v[222:225], v[62:63], off offset:144
	global_load_dwordx4 v[226:229], v[62:63], off offset:128
	s_waitcnt vmcnt(0)
	v_cvt_pk_bf16_f32 v181, v226, s0
	v_cvt_pk_bf16_f32 v227, v227, v228
	v_perm_b32 v226, v227, v181, s87
	v_cvt_pk_bf16_f32 v181, v229, v222
	v_cvt_pk_bf16_f32 v222, v223, v224
	v_alignbit_b32 v227, v181, v227, 16
	v_alignbit_b32 v228, v222, v181, 16
	v_cvt_pk_bf16_f32 v181, v225, s0
	v_alignbit_b32 v229, v181, v222, 16
	s_nop 1
	v_mfma_f32_16x16x32_bf16 v[32:35], v[226:229], v[0:3], v[32:35]
	global_load_dwordx4 v[222:225], v[110:111], off offset:16
	global_load_dwordx4 v[226:229], v[110:111], off
	s_waitcnt vmcnt(0)
	v_cvt_pk_bf16_f32 v181, v226, s0
	v_cvt_pk_bf16_f32 v227, v227, v228
	v_perm_b32 v226, v227, v181, s87
	v_cvt_pk_bf16_f32 v181, v229, v222
	v_cvt_pk_bf16_f32 v222, v223, v224
	v_alignbit_b32 v227, v181, v227, 16
	v_alignbit_b32 v228, v222, v181, 16
	v_cvt_pk_bf16_f32 v181, v225, s0
	v_alignbit_b32 v229, v181, v222, 16
	v_pk_mul_f32 v[34:35], v[198:199], v[34:35] op_sel_hi:[0,1]
	v_pk_mul_f32 v[32:33], v[198:199], v[32:33] op_sel_hi:[0,1]
	v_mfma_f32_16x16x32_bf16 v[28:31], v[226:229], v[0:3], v[28:31]
	global_load_dwordx4 v[222:225], v[112:113], off offset:16
	global_load_dwordx4 v[226:229], v[112:113], off
	s_waitcnt vmcnt(0)
	v_cvt_pk_bf16_f32 v181, v226, s0
	v_cvt_pk_bf16_f32 v227, v227, v228
	v_perm_b32 v226, v227, v181, s87
	v_cvt_pk_bf16_f32 v181, v229, v222
	v_cvt_pk_bf16_f32 v222, v223, v224
	v_alignbit_b32 v227, v181, v227, 16
	v_alignbit_b32 v228, v222, v181, 16
	v_cvt_pk_bf16_f32 v181, v225, s0
	v_alignbit_b32 v229, v181, v222, 16
	v_pk_mul_f32 v[30:31], v[198:199], v[30:31] op_sel_hi:[0,1]
	v_pk_mul_f32 v[28:29], v[198:199], v[28:29] op_sel_hi:[0,1]
	v_mfma_f32_16x16x32_bf16 v[24:27], v[226:229], v[0:3], v[24:27]
	global_load_dwordx4 v[222:225], v[114:115], off offset:16
	global_load_dwordx4 v[226:229], v[114:115], off
	s_waitcnt vmcnt(0)
	v_cvt_pk_bf16_f32 v181, v226, s0
	v_cvt_pk_bf16_f32 v227, v227, v228
	v_perm_b32 v226, v227, v181, s87
	v_cvt_pk_bf16_f32 v181, v229, v222
	v_cvt_pk_bf16_f32 v222, v223, v224
	v_alignbit_b32 v227, v181, v227, 16
	v_alignbit_b32 v228, v222, v181, 16
	v_cvt_pk_bf16_f32 v181, v225, s0
	v_alignbit_b32 v229, v181, v222, 16
	v_pk_mul_f32 v[26:27], v[198:199], v[26:27] op_sel_hi:[0,1]
	v_pk_mul_f32 v[24:25], v[198:199], v[24:25] op_sel_hi:[0,1]
	v_mfma_f32_16x16x32_bf16 v[8:11], v[226:229], v[0:3], v[8:11]
	global_load_dwordx4 v[222:225], v[116:117], off offset:16
	global_load_dwordx4 v[226:229], v[116:117], off
	s_waitcnt vmcnt(0)
	v_cvt_pk_bf16_f32 v181, v226, s0
	v_cvt_pk_bf16_f32 v227, v227, v228
	v_perm_b32 v226, v227, v181, s87
	v_cvt_pk_bf16_f32 v181, v229, v222
	v_cvt_pk_bf16_f32 v222, v223, v224
	v_alignbit_b32 v227, v181, v227, 16
	v_alignbit_b32 v228, v222, v181, 16
	v_cvt_pk_bf16_f32 v181, v225, s0
	v_alignbit_b32 v229, v181, v222, 16
	v_pk_mul_f32 v[10:11], v[198:199], v[10:11] op_sel_hi:[0,1]
	v_pk_mul_f32 v[8:9], v[198:199], v[8:9] op_sel_hi:[0,1]
	v_mfma_f32_16x16x32_bf16 v[12:15], v[226:229], v[0:3], v[12:15]
	global_load_dwordx4 v[222:225], v[118:119], off offset:16
	global_load_dwordx4 v[226:229], v[118:119], off
	s_waitcnt vmcnt(0)
	v_cvt_pk_bf16_f32 v181, v226, s0
	v_cvt_pk_bf16_f32 v227, v227, v228
	v_perm_b32 v226, v227, v181, s87
	v_cvt_pk_bf16_f32 v181, v229, v222
	v_cvt_pk_bf16_f32 v222, v223, v224
	v_alignbit_b32 v227, v181, v227, 16
	v_alignbit_b32 v228, v222, v181, 16
	v_cvt_pk_bf16_f32 v181, v225, s0
	v_alignbit_b32 v229, v181, v222, 16
	v_pk_mul_f32 v[14:15], v[198:199], v[14:15] op_sel_hi:[0,1]
	v_pk_mul_f32 v[12:13], v[198:199], v[12:13] op_sel_hi:[0,1]
	v_mfma_f32_16x16x32_bf16 v[16:19], v[226:229], v[0:3], v[16:19]
	global_load_dwordx4 v[222:225], v[120:121], off offset:16
	global_load_dwordx4 v[226:229], v[120:121], off
	s_waitcnt vmcnt(0)
	v_cvt_pk_bf16_f32 v181, v226, s0
	v_cvt_pk_bf16_f32 v227, v227, v228
	v_perm_b32 v226, v227, v181, s87
	v_cvt_pk_bf16_f32 v181, v229, v222
	v_cvt_pk_bf16_f32 v222, v223, v224
	v_alignbit_b32 v227, v181, v227, 16
	v_alignbit_b32 v228, v222, v181, 16
	v_cvt_pk_bf16_f32 v181, v225, s0
	v_alignbit_b32 v229, v181, v222, 16
	v_pk_mul_f32 v[18:19], v[198:199], v[18:19] op_sel_hi:[0,1]
	v_pk_mul_f32 v[16:17], v[198:199], v[16:17] op_sel_hi:[0,1]
	v_mfma_f32_16x16x32_bf16 v[20:23], v[226:229], v[0:3], v[20:23]
	global_load_dwordx4 v[222:225], v[122:123], off offset:16
	global_load_dwordx4 v[226:229], v[122:123], off
	ds_read_b128 v[230:233], v48 offset:4288
	s_nop 4
	v_pk_mul_f32 v[22:23], v[198:199], v[22:23] op_sel_hi:[0,1]
	v_pk_mul_f32 v[20:21], v[198:199], v[20:21] op_sel_hi:[0,1]
	s_waitcnt vmcnt(0)
	v_cvt_pk_bf16_f32 v181, v226, s0
	v_cvt_pk_bf16_f32 v227, v227, v228
	v_perm_b32 v226, v227, v181, s87
	v_cvt_pk_bf16_f32 v181, v229, v222
	v_cvt_pk_bf16_f32 v222, v223, v224
	v_alignbit_b32 v227, v181, v227, 16
	v_alignbit_b32 v228, v222, v181, 16
	v_cvt_pk_bf16_f32 v181, v225, s0
	v_alignbit_b32 v229, v181, v222, 16
	global_load_dwordx4 v[222:225], v[58:59], off
	s_mov_b64 s[0:1], 0x6c01020
	v_mfma_f32_16x16x32_bf16 v[0:3], v[226:229], v[0:3], v[4:7]
	s_nop 2
	ds_read_b128 v[4:7], v48 offset:4096
	s_waitcnt vmcnt(0) lgkmcnt(0)
	v_mfma_f32_16x16x32_bf16 v[32:35], v[222:225], v[4:7], v[32:35]
	global_load_dwordx4 v[222:225], v[124:125], off
	s_nop 0
	v_pk_mul_f32 v[2:3], v[198:199], v[2:3] op_sel_hi:[0,1]
	v_pk_mul_f32 v[0:1], v[198:199], v[0:1] op_sel_hi:[0,1]
	s_waitcnt vmcnt(0)
	v_mfma_f32_16x16x32_bf16 v[28:31], v[222:225], v[4:7], v[28:31]
	global_load_dwordx4 v[222:225], v[126:127], off
	s_waitcnt vmcnt(0)
	v_mfma_f32_16x16x32_bf16 v[24:27], v[222:225], v[4:7], v[24:27]
	global_load_dwordx4 v[222:225], v[128:129], off
	s_waitcnt vmcnt(0)
	v_mfma_f32_16x16x32_bf16 v[8:11], v[222:225], v[4:7], v[8:11]
	global_load_dwordx4 v[222:225], v[130:131], off
	s_waitcnt vmcnt(0)
	v_mfma_f32_16x16x32_bf16 v[12:15], v[222:225], v[4:7], v[12:15]
	global_load_dwordx4 v[222:225], v[132:133], off
	s_waitcnt vmcnt(0)
	v_mfma_f32_16x16x32_bf16 v[16:19], v[222:225], v[4:7], v[16:19]
	global_load_dwordx4 v[222:225], v[134:135], off
	s_waitcnt vmcnt(0)
	v_mfma_f32_16x16x32_bf16 v[20:23], v[222:225], v[4:7], v[20:23]
	global_load_dwordx4 v[222:225], v[136:137], off
	s_waitcnt vmcnt(0)
	v_mfma_f32_16x16x32_bf16 v[0:3], v[222:225], v[4:7], v[0:3]
	global_load_dwordx4 v[222:225], v[58:59], off offset:64
	ds_read_b128 v[4:7], v48 offset:4160
	s_waitcnt vmcnt(0) lgkmcnt(0)
	v_mfma_f32_16x16x32_bf16 v[32:35], v[222:225], v[4:7], v[32:35]
	global_load_dwordx4 v[222:225], v[138:139], off
	s_waitcnt vmcnt(0)
	v_mfma_f32_16x16x32_bf16 v[28:31], v[222:225], v[4:7], v[28:31]
	global_load_dwordx4 v[222:225], v[140:141], off
	s_waitcnt vmcnt(0)
	v_mfma_f32_16x16x32_bf16 v[24:27], v[222:225], v[4:7], v[24:27]
	global_load_dwordx4 v[222:225], v[142:143], off
	s_waitcnt vmcnt(0)
	v_mfma_f32_16x16x32_bf16 v[8:11], v[222:225], v[4:7], v[8:11]
	global_load_dwordx4 v[222:225], v[144:145], off
	s_waitcnt vmcnt(0)
	v_mfma_f32_16x16x32_bf16 v[12:15], v[222:225], v[4:7], v[12:15]
	global_load_dwordx4 v[222:225], v[146:147], off
	s_waitcnt vmcnt(0)
	v_mfma_f32_16x16x32_bf16 v[16:19], v[222:225], v[4:7], v[16:19]
	global_load_dwordx4 v[222:225], v[148:149], off
	s_waitcnt vmcnt(0)
	v_mfma_f32_16x16x32_bf16 v[20:23], v[222:225], v[4:7], v[20:23]
	global_load_dwordx4 v[222:225], v[150:151], off
	s_waitcnt vmcnt(0)
	v_mfma_f32_16x16x32_bf16 v[0:3], v[222:225], v[4:7], v[0:3]
	global_load_dwordx4 v[222:225], v[58:59], off offset:128
	ds_read_b128 v[4:7], v48 offset:4224
	s_waitcnt vmcnt(0) lgkmcnt(0)
	v_mfma_f32_16x16x32_bf16 v[32:35], v[222:225], v[4:7], v[32:35]
	global_load_dwordx4 v[222:225], v[152:153], off
	s_waitcnt vmcnt(0)
	v_mfma_f32_16x16x32_bf16 v[28:31], v[222:225], v[4:7], v[28:31]
	global_load_dwordx4 v[222:225], v[154:155], off
	s_waitcnt vmcnt(0)
	v_mfma_f32_16x16x32_bf16 v[24:27], v[222:225], v[4:7], v[24:27]
	global_load_dwordx4 v[222:225], v[156:157], off
	s_waitcnt vmcnt(0)
	v_mfma_f32_16x16x32_bf16 v[8:11], v[222:225], v[4:7], v[8:11]
	global_load_dwordx4 v[222:225], v[158:159], off
	s_waitcnt vmcnt(0)
	v_mfma_f32_16x16x32_bf16 v[12:15], v[222:225], v[4:7], v[12:15]
	global_load_dwordx4 v[222:225], v[160:161], off
	s_waitcnt vmcnt(0)
	v_mfma_f32_16x16x32_bf16 v[222:225], v[222:225], v[4:7], v[16:19]
	s_nop 2
	global_load_dwordx4 v[16:19], v[162:163], off
	s_waitcnt vmcnt(0)
	v_mfma_f32_16x16x32_bf16 v[226:229], v[16:19], v[4:7], v[20:23]
	global_load_dwordx4 v[16:19], v[164:165], off
	s_waitcnt vmcnt(0)
	v_mfma_f32_16x16x32_bf16 v[0:3], v[16:19], v[4:7], v[0:3]
	global_load_dwordx4 v[4:7], v[58:59], off offset:192
	s_waitcnt vmcnt(0)
	v_mfma_f32_16x16x32_bf16 v[32:35], v[4:7], v[230:233], v[32:35]
	global_load_dwordx4 v[4:7], v[166:167], off
	s_waitcnt vmcnt(0)
	v_mfma_f32_16x16x32_bf16 v[28:31], v[4:7], v[230:233], v[28:31]
	global_load_dwordx4 v[4:7], v[168:169], off
	s_waitcnt vmcnt(0)
	v_mfma_f32_16x16x32_bf16 v[24:27], v[4:7], v[230:233], v[24:27]
	global_load_dwordx4 v[4:7], v[170:171], off
	s_waitcnt vmcnt(0)
	v_mfma_f32_16x16x32_bf16 v[20:23], v[4:7], v[230:233], v[8:11]
	global_load_dwordx4 v[4:7], v[172:173], off
	s_waitcnt vmcnt(0)
	v_mfma_f32_16x16x32_bf16 v[16:19], v[4:7], v[230:233], v[12:15]
	global_load_dwordx4 v[4:7], v[174:175], off
	s_nop 1
	global_load_dwordx4 v[12:15], v[178:179], off
	s_waitcnt vmcnt(1)
	v_mfma_f32_16x16x32_bf16 v[8:11], v[4:7], v[230:233], v[222:225]
	global_load_dwordx4 v[4:7], v[176:177], off
	s_waitcnt vmcnt(1)
	v_mfma_f32_16x16x32_bf16 v[12:15], v[12:15], v[230:233], v[0:3]
	s_nop 2
	global_load_dwordx4 v[0:3], v[238:239], off
	s_waitcnt vmcnt(1)
	v_mfma_f32_16x16x32_bf16 v[4:7], v[4:7], v[230:233], v[226:229]
	global_load_dwordx4 v[222:225], v[60:61], off offset:48
	s_nop 1
	global_load_dwordx4 v[226:229], v[60:61], off offset:32
	global_load_dwordx4 v[230:233], v[60:61], off offset:16
	global_load_dwordx4 v[234:237], v[60:61], off
	s_waitcnt vmcnt(4)
	v_lshlrev_b32_e32 v48, 16, v0
	v_and_b32_e32 v0, 0xffff0000, v0
	s_waitcnt vmcnt(0)
	v_mul_f32_e32 v235, v235, v0
	v_lshlrev_b32_e32 v0, 16, v1
	v_mul_f32_e32 v181, v234, v48
	v_mul_f32_e32 v241, v236, v0
	v_and_b32_e32 v0, 0xffff0000, v1
	v_mov_b32_e32 v48, v182
	v_mul_f32_e32 v1, v237, v0
	v_lshlrev_b32_e32 v0, 16, v2
	v_pk_add_f32 v[180:181], v[48:49], v[180:181]
	v_mov_b32_e32 v234, v183
	v_mul_f32_e32 v237, v230, v0
	v_and_b32_e32 v0, 0xffff0000, v2
	v_pk_add_f32 v[180:181], v[234:235], v[180:181]
	v_mul_f32_e32 v231, v231, v0
	v_pk_add_f32 v[180:181], v[240:241], v[180:181]
	v_mov_b32_e32 v0, v185
	v_pk_add_f32 v[0:1], v[0:1], v[180:181]
	v_mov_b32_e32 v236, v186
	v_pk_add_f32 v[0:1], v[236:237], v[0:1]
	v_mov_b32_e32 v230, v187
	v_pk_add_f32 v[180:181], v[230:231], v[0:1]
	v_lshlrev_b32_e32 v0, 16, v3
	v_mul_f32_e32 v183, v232, v0
	v_and_b32_e32 v0, 0xffff0000, v3
	v_mul_f32_e32 v185, v233, v0
	global_load_dwordx4 v[0:3], v[238:239], off offset:16
	v_mov_b32_e32 v182, v188
	v_pk_add_f32 v[180:181], v[182:183], v[180:181]
	v_mov_b32_e32 v186, v190
	v_pk_add_f32 v[180:181], v[184:185], v[180:181]
	v_mov_b32_e32 v230, v192
	v_mov_b32_e32 v232, v196
	s_waitcnt vmcnt(0)
	v_lshlrev_b32_e32 v48, 16, v0
	v_and_b32_e32 v0, 0xffff0000, v0
	v_mul_f32_e32 v227, v227, v0
	v_lshlrev_b32_e32 v0, 16, v1
	v_mul_f32_e32 v231, v228, v0
	v_and_b32_e32 v0, 0xffff0000, v1
	v_mul_f32_e32 v1, v229, v0
	v_lshlrev_b32_e32 v0, 16, v2
	v_mul_f32_e32 v187, v226, v48
	v_mul_f32_e32 v229, v222, v0
	v_and_b32_e32 v0, 0xffff0000, v2
	v_mul_f32_e32 v223, v223, v0
	v_lshlrev_b32_e32 v0, 16, v3
	v_pk_add_f32 v[180:181], v[186:187], v[180:181]
	v_mov_b32_e32 v226, v191
	v_mul_f32_e32 v233, v224, v0
	v_and_b32_e32 v0, 0xffff0000, v3
	v_pk_add_f32 v[180:181], v[226:227], v[180:181]
	v_mul_f32_e32 v3, v225, v0
	v_pk_add_f32 v[180:181], v[230:231], v[180:181]
	v_mov_b32_e32 v0, v193
	v_pk_add_f32 v[0:1], v[0:1], v[180:181]
	v_mov_b32_e32 v228, v194
	v_pk_add_f32 v[0:1], v[228:229], v[0:1]
	v_mov_b32_e32 v222, v195
	v_pk_add_f32 v[0:1], v[222:223], v[0:1]
	v_mov_b32_e32 v2, v197
	v_pk_add_f32 v[0:1], v[232:233], v[0:1]
	v_lshl_add_u64 v[180:181], v[66:67], 0, s[22:23]
	v_pk_add_f32 v[0:1], v[2:3], v[0:1]
	ds_bpermute_b32 v2, v217, v0
	ds_bpermute_b32 v3, v217, v1
	s_waitcnt lgkmcnt(0)
	v_pk_add_f32 v[0:1], v[0:1], v[2:3]
	ds_bpermute_b32 v2, v218, v0
	ds_bpermute_b32 v3, v218, v1
	s_waitcnt lgkmcnt(0)
	v_pk_add_f32 v[0:1], v[0:1], v[2:3]
	s_nop 0
	v_fmac_f32_e32 v0, v198, v1
	ds_read_b32 v1, v220 offset:1024
	s_waitcnt lgkmcnt(0)
	v_add_f32_e32 v1, v221, v1
	v_mul_f32_e32 v1, 0xbfb8aa3b, v1
	v_exp_f32_e32 v1, v1
	s_nop 0
	v_max_f32_e64 v0, |v0|, v1
	v_rcp_f32_e32 v48, v0
	v_lshl_add_u64 v[0:1], s[2:3], 0, v[40:41]
	v_lshl_add_u64 v[182:183], v[0:1], 0, s[0:1]
	s_mov_b32 s0, 0x6c01000
	v_add_co_u32_e64 v0, s[0:1], s0, v0
	v_pk_mul_f32 v[220:221], v[32:33], v[48:49] op_sel_hi:[1,0]
	s_nop 0
	v_addc_co_u32_e64 v1, s[0:1], 0, v1, s[0:1]
	global_load_dwordx2 v[0:1], v[0:1], off offset:32
	v_add_f32_e32 v198, 0, v220
	v_add_f32_e32 v198, v221, v198
	v_pk_mul_f32 v[220:221], v[28:29], v[48:49] op_sel_hi:[1,0]
	v_pk_mul_f32 v[194:195], v[4:5], v[48:49] op_sel_hi:[1,0]
	v_pk_mul_f32 v[192:193], v[6:7], v[48:49] op_sel_hi:[1,0]
	v_pk_mul_f32 v[190:191], v[12:13], v[48:49] op_sel_hi:[1,0]
	v_pk_mul_f32 v[188:189], v[14:15], v[48:49] op_sel_hi:[1,0]
	s_mov_b32 s0, 0x800000
	s_waitcnt vmcnt(0)
	v_lshlrev_b32_e32 v184, 16, v0
	v_mul_f32_e32 v184, 0xbfb8aa3b, v184
	v_exp_f32_e32 v184, v184
	v_and_b32_e32 v185, 0xffff0000, v0
	v_lshlrev_b32_e32 v196, 16, v1
	v_and_b32_e32 v197, 0xffff0000, v1
	v_add_f32_e32 v184, 1.0, v184
	v_rcp_f32_e32 v186, v184
	v_mul_f32_e32 v184, 0xbfb8aa3b, v185
	v_exp_f32_e32 v184, v184
	v_mul_f32_e32 v185, 0xbfb8aa3b, v197
	global_load_dwordx4 v[0:3], v[64:65], off
	v_exp_f32_e32 v185, v185
	v_add_f32_e32 v184, 1.0, v184
	v_rcp_f32_e32 v187, v184
	v_mul_f32_e32 v184, 0xbfb8aa3b, v196
	v_pk_mul_f32 v[196:197], v[34:35], v[48:49] op_sel_hi:[1,0]
	v_exp_f32_e32 v184, v184
	v_add_f32_e32 v196, v196, v198
	v_add_f32_e32 v198, v197, v196
	v_add_f32_e32 v198, v220, v198
	v_pk_mul_f32 v[196:197], v[30:31], v[48:49] op_sel_hi:[1,0]
	v_add_f32_e32 v198, v221, v198
	v_add_f32_e32 v196, v196, v198
	v_add_f32_e32 v198, v197, v196
	v_pk_mul_f32 v[220:221], v[24:25], v[48:49] op_sel_hi:[1,0]
	v_pk_mul_f32 v[196:197], v[26:27], v[48:49] op_sel_hi:[1,0]
	v_add_f32_e32 v198, v220, v198
	v_add_f32_e32 v198, v221, v198
	v_add_f32_e32 v196, v196, v198
	v_add_f32_e32 v198, v197, v196
	v_pk_mul_f32 v[220:221], v[20:21], v[48:49] op_sel_hi:[1,0]
	v_pk_mul_f32 v[196:197], v[22:23], v[48:49] op_sel_hi:[1,0]
	v_add_f32_e32 v198, v220, v198
	v_add_f32_e32 v198, v221, v198
	v_add_f32_e32 v196, v196, v198
	v_add_f32_e32 v198, v197, v196
	v_pk_mul_f32 v[220:221], v[16:17], v[48:49] op_sel_hi:[1,0]
	v_pk_mul_f32 v[196:197], v[18:19], v[48:49] op_sel_hi:[1,0]
	v_add_f32_e32 v198, v220, v198
	v_add_f32_e32 v198, v221, v198
	v_add_f32_e32 v196, v196, v198
	v_add_f32_e32 v198, v197, v196
	v_pk_mul_f32 v[220:221], v[8:9], v[48:49] op_sel_hi:[1,0]
	v_pk_mul_f32 v[196:197], v[10:11], v[48:49] op_sel_hi:[1,0]
	v_add_f32_e32 v198, v220, v198
	v_add_f32_e32 v198, v221, v198
	v_add_f32_e32 v196, v196, v198
	v_add_f32_e32 v196, v197, v196
	v_add_f32_e32 v194, v194, v196
	v_add_f32_e32 v194, v195, v194
	v_add_f32_e32 v192, v192, v194
	v_add_f32_e32 v192, v193, v192
	v_add_f32_e32 v190, v190, v192
	v_add_f32_e32 v190, v191, v190
	v_add_f32_e32 v188, v188, v190
	v_add_f32_e32 v188, v189, v188
	ds_bpermute_b32 v189, v217, v188
	v_add_f32_e32 v184, 1.0, v184
	v_add_f32_e32 v185, 1.0, v185
	v_rcp_f32_e32 v184, v184
	v_rcp_f32_e32 v185, v185
	s_waitcnt lgkmcnt(0)
	v_add_f32_e32 v188, v188, v189
	ds_bpermute_b32 v189, v218, v188
	s_waitcnt lgkmcnt(0)
	v_add_f32_e32 v188, v188, v189
	v_mul_f32_e32 v192, 0x3c000000, v188
	v_pk_fma_f32 v[190:191], v[32:33], v[48:49], v[192:193] op_sel_hi:[1,0,0] neg_lo:[0,0,1] neg_hi:[0,0,1]
	v_pk_fma_f32 v[188:189], v[34:35], v[48:49], v[192:193] op_sel_hi:[1,0,0] neg_lo:[0,0,1] neg_hi:[0,0,1]
	v_pk_mul_f32 v[194:195], v[190:191], v[190:191]
	v_pk_mul_f32 v[196:197], v[188:189], v[188:189]
	v_pk_fma_f32 v[34:35], v[28:29], v[48:49], v[192:193] op_sel_hi:[1,0,0] neg_lo:[0,0,1] neg_hi:[0,0,1]
	v_pk_fma_f32 v[32:33], v[30:31], v[48:49], v[192:193] op_sel_hi:[1,0,0] neg_lo:[0,0,1] neg_hi:[0,0,1]
	v_pk_fma_f32 v[30:31], v[24:25], v[48:49], v[192:193] op_sel_hi:[1,0,0] neg_lo:[0,0,1] neg_hi:[0,0,1]
	v_pk_fma_f32 v[28:29], v[26:27], v[48:49], v[192:193] op_sel_hi:[1,0,0] neg_lo:[0,0,1] neg_hi:[0,0,1]
	v_pk_fma_f32 v[26:27], v[20:21], v[48:49], v[192:193] op_sel_hi:[1,0,0] neg_lo:[0,0,1] neg_hi:[0,0,1]
	v_pk_fma_f32 v[24:25], v[22:23], v[48:49], v[192:193] op_sel_hi:[1,0,0] neg_lo:[0,0,1] neg_hi:[0,0,1]
	v_pk_fma_f32 v[22:23], v[16:17], v[48:49], v[192:193] op_sel_hi:[1,0,0] neg_lo:[0,0,1] neg_hi:[0,0,1]
	v_pk_fma_f32 v[20:21], v[18:19], v[48:49], v[192:193] op_sel_hi:[1,0,0] neg_lo:[0,0,1] neg_hi:[0,0,1]
	v_pk_fma_f32 v[18:19], v[8:9], v[48:49], v[192:193] op_sel_hi:[1,0,0] neg_lo:[0,0,1] neg_hi:[0,0,1]
	v_pk_fma_f32 v[16:17], v[10:11], v[48:49], v[192:193] op_sel_hi:[1,0,0] neg_lo:[0,0,1] neg_hi:[0,0,1]
	v_pk_fma_f32 v[10:11], v[12:13], v[48:49], v[192:193] op_sel_hi:[1,0,0] neg_lo:[0,0,1] neg_hi:[0,0,1]
	v_pk_fma_f32 v[8:9], v[14:15], v[48:49], v[192:193] op_sel_hi:[1,0,0] neg_lo:[0,0,1] neg_hi:[0,0,1]
	v_pk_fma_f32 v[6:7], v[6:7], v[48:49], v[192:193] op_sel_hi:[1,0,0] neg_lo:[0,0,1] neg_hi:[0,0,1]
	v_pk_fma_f32 v[4:5], v[4:5], v[48:49], v[192:193] op_sel_hi:[1,0,0] neg_lo:[0,0,1] neg_hi:[0,0,1]
	v_add_f32_e32 v48, v194, v195
	v_add_f32_e32 v48, v196, v48
	v_pk_mul_f32 v[220:221], v[34:35], v[34:35]
	v_add_f32_e32 v48, v197, v48
	v_add_f32_e32 v48, v220, v48
	v_pk_mul_f32 v[222:223], v[32:33], v[32:33]
	v_add_f32_e32 v48, v221, v48
	v_add_f32_e32 v48, v222, v48
	v_pk_mul_f32 v[224:225], v[30:31], v[30:31]
	v_add_f32_e32 v48, v223, v48
	v_add_f32_e32 v48, v224, v48
	v_pk_mul_f32 v[226:227], v[28:29], v[28:29]
	v_add_f32_e32 v48, v225, v48
	v_add_f32_e32 v48, v226, v48
	v_pk_mul_f32 v[228:229], v[26:27], v[26:27]
	v_add_f32_e32 v48, v227, v48
	v_add_f32_e32 v48, v228, v48
	v_pk_mul_f32 v[230:231], v[24:25], v[24:25]
	v_add_f32_e32 v48, v229, v48
	v_add_f32_e32 v48, v230, v48
	v_pk_mul_f32 v[232:233], v[22:23], v[22:23]
	v_add_f32_e32 v48, v231, v48
	v_add_f32_e32 v48, v232, v48
	v_pk_mul_f32 v[234:235], v[20:21], v[20:21]
	v_add_f32_e32 v48, v233, v48
	v_add_f32_e32 v48, v234, v48
	v_pk_mul_f32 v[236:237], v[18:19], v[18:19]
	v_add_f32_e32 v48, v235, v48
	v_add_f32_e32 v48, v236, v48
	v_pk_mul_f32 v[238:239], v[16:17], v[16:17]
	v_add_f32_e32 v48, v237, v48
	v_add_f32_e32 v48, v238, v48
	v_pk_mul_f32 v[192:193], v[4:5], v[4:5]
	v_add_f32_e32 v48, v239, v48
	v_add_f32_e32 v48, v192, v48
	v_pk_mul_f32 v[240:241], v[6:7], v[6:7]
	v_add_f32_e32 v48, v193, v48
	v_add_f32_e32 v48, v240, v48
	v_pk_mul_f32 v[12:13], v[10:11], v[10:11]
	v_add_f32_e32 v48, v241, v48
	v_add_f32_e32 v12, v12, v48
	v_pk_mul_f32 v[14:15], v[8:9], v[8:9]
	v_add_f32_e32 v12, v13, v12
	v_add_f32_e32 v12, v14, v12
	v_add_f32_e32 v12, v15, v12
	ds_bpermute_b32 v13, v217, v12
	s_waitcnt lgkmcnt(0)
	v_add_f32_e32 v12, v12, v13
	ds_bpermute_b32 v13, v218, v12
	s_waitcnt lgkmcnt(0)
	v_add_f32_e32 v12, v12, v13
	v_fmamk_f32 v12, v12, 0x3c000000, v206
	v_cmp_gt_f32_e64 s[22:23], s0, v12
	v_mul_f32_e32 v13, 0x4b800000, v12
	s_mov_b64 s[0:1], 0
	v_cndmask_b32_e64 v12, v12, v13, s[22:23]
	v_rsq_f32_e32 v12, v12
	s_nop 0
	v_mul_f32_e32 v13, 0x45800000, v12
	v_cndmask_b32_e64 v12, v12, v13, s[22:23]
	v_pk_mul_f32 v[14:15], v[190:191], v[12:13] op_sel_hi:[1,0]
	s_waitcnt vmcnt(0)
	v_pk_mul_f32 v[0:1], v[0:1], v[14:15]
	v_pk_mul_f32 v[14:15], v[188:189], v[12:13] op_sel_hi:[1,0]
	v_pk_mul_f32 v[0:1], v[186:187], v[0:1]
	v_pk_mul_f32 v[2:3], v[2:3], v[14:15]
	v_cvt_pk_bf16_f32 v0, v0, v1
	v_pk_mul_f32 v[2:3], v[184:185], v[2:3]
	s_nop 0
	v_cvt_pk_bf16_f32 v1, v2, v3
	global_store_dwordx2 v[180:181], v[0:1], off
	global_load_dwordx2 v[244:245], v[182:183], off offset:32
	global_load_dwordx4 v[0:3], v[64:65], off offset:64
	s_waitcnt vmcnt(0)
	v_lshlrev_b32_e32 v13, 16, v244
	v_and_b32_e32 v15, 0xffff0000, v244
	v_lshlrev_b32_e32 v48, 16, v245
	v_and_b32_e32 v184, 0xffff0000, v245
	v_mul_f32_e32 v13, 0xbfb8aa3b, v13
	v_exp_f32_e32 v13, v13
	s_nop 0
	v_add_f32_e32 v13, 1.0, v13
	v_rcp_f32_e32 v14, v13
	v_pk_mul_f32 v[34:35], v[34:35], v[12:13] op_sel_hi:[1,0]
	v_mul_f32_e32 v13, 0xbfb8aa3b, v15
	v_exp_f32_e32 v13, v13
	s_waitcnt vmcnt(0)
	v_pk_mul_f32 v[0:1], v[0:1], v[34:35]
	v_add_f32_e32 v13, 1.0, v13
	v_rcp_f32_e32 v15, v13
	v_mul_f32_e32 v13, 0xbfb8aa3b, v48
	v_exp_f32_e32 v13, v13
	v_pk_mul_f32 v[0:1], v[14:15], v[0:1]
	s_nop 0
	v_cvt_pk_bf16_f32 v0, v0, v1
	v_add_f32_e32 v13, 1.0, v13
	v_rcp_f32_e32 v14, v13
	v_pk_mul_f32 v[32:33], v[32:33], v[12:13] op_sel_hi:[1,0]
	v_mul_f32_e32 v13, 0xbfb8aa3b, v184
	v_exp_f32_e32 v13, v13
	v_pk_mul_f32 v[2:3], v[2:3], v[32:33]
	v_add_f32_e32 v13, 1.0, v13
	v_rcp_f32_e32 v15, v13
	s_nop 0
	v_pk_mul_f32 v[2:3], v[14:15], v[2:3]
	s_nop 0
	v_cvt_pk_bf16_f32 v1, v2, v3
	global_store_dwordx2 v[180:181], v[0:1], off offset:32
	global_load_dwordx2 v[244:245], v[182:183], off offset:64
	global_load_dwordx4 v[0:3], v[64:65], off offset:128
	s_waitcnt vmcnt(0)
	v_lshlrev_b32_e32 v13, 16, v244
	v_and_b32_e32 v15, 0xffff0000, v244
	v_lshlrev_b32_e32 v32, 16, v245
	v_and_b32_e32 v33, 0xffff0000, v245
	v_mul_f32_e32 v13, 0xbfb8aa3b, v13
	v_exp_f32_e32 v13, v13
	s_nop 0
	v_add_f32_e32 v13, 1.0, v13
	v_rcp_f32_e32 v14, v13
	v_pk_mul_f32 v[30:31], v[30:31], v[12:13] op_sel_hi:[1,0]
	v_mul_f32_e32 v13, 0xbfb8aa3b, v15
	v_exp_f32_e32 v13, v13
	s_waitcnt vmcnt(0)
	v_pk_mul_f32 v[0:1], v[0:1], v[30:31]
	v_add_f32_e32 v13, 1.0, v13
	v_rcp_f32_e32 v15, v13
	v_mul_f32_e32 v13, 0xbfb8aa3b, v32
	v_exp_f32_e32 v13, v13
	v_pk_mul_f32 v[0:1], v[14:15], v[0:1]
	s_nop 0
	v_cvt_pk_bf16_f32 v0, v0, v1
	v_add_f32_e32 v13, 1.0, v13
	v_rcp_f32_e32 v14, v13
	v_pk_mul_f32 v[28:29], v[28:29], v[12:13] op_sel_hi:[1,0]
	v_mul_f32_e32 v13, 0xbfb8aa3b, v33
	v_exp_f32_e32 v13, v13
	v_pk_mul_f32 v[2:3], v[2:3], v[28:29]
	v_add_f32_e32 v13, 1.0, v13
	v_rcp_f32_e32 v15, v13
	s_nop 0
	v_pk_mul_f32 v[2:3], v[14:15], v[2:3]
	s_nop 0
	v_cvt_pk_bf16_f32 v1, v2, v3
	global_store_dwordx2 v[180:181], v[0:1], off offset:64
	global_load_dwordx2 v[244:245], v[182:183], off offset:96
	global_load_dwordx4 v[0:3], v[64:65], off offset:192
	s_waitcnt vmcnt(0)
	v_lshlrev_b32_e32 v13, 16, v244
	v_and_b32_e32 v15, 0xffff0000, v244
	v_lshlrev_b32_e32 v28, 16, v245
	v_and_b32_e32 v29, 0xffff0000, v245
	v_mul_f32_e32 v13, 0xbfb8aa3b, v13
	v_exp_f32_e32 v13, v13
	s_nop 0
	v_add_f32_e32 v13, 1.0, v13
	v_rcp_f32_e32 v14, v13
	v_pk_mul_f32 v[26:27], v[26:27], v[12:13] op_sel_hi:[1,0]
	v_mul_f32_e32 v13, 0xbfb8aa3b, v15
	v_exp_f32_e32 v13, v13
	s_waitcnt vmcnt(0)
	v_pk_mul_f32 v[0:1], v[0:1], v[26:27]
	v_add_f32_e32 v13, 1.0, v13
	v_rcp_f32_e32 v15, v13
	v_mul_f32_e32 v13, 0xbfb8aa3b, v28
	v_exp_f32_e32 v13, v13
	v_pk_mul_f32 v[0:1], v[14:15], v[0:1]
	s_nop 0
	v_cvt_pk_bf16_f32 v0, v0, v1
	v_add_f32_e32 v13, 1.0, v13
	v_rcp_f32_e32 v14, v13
	v_pk_mul_f32 v[24:25], v[24:25], v[12:13] op_sel_hi:[1,0]
	v_mul_f32_e32 v13, 0xbfb8aa3b, v29
	v_exp_f32_e32 v13, v13
	v_pk_mul_f32 v[2:3], v[2:3], v[24:25]
	v_add_f32_e32 v13, 1.0, v13
	v_rcp_f32_e32 v15, v13
	s_nop 0
	v_pk_mul_f32 v[2:3], v[14:15], v[2:3]
	s_nop 0
	v_cvt_pk_bf16_f32 v1, v2, v3
	global_store_dwordx2 v[180:181], v[0:1], off offset:96
	global_load_dwordx2 v[244:245], v[182:183], off offset:128
	global_load_dwordx4 v[0:3], v[64:65], off offset:256
	s_waitcnt vmcnt(0)
	v_lshlrev_b32_e32 v13, 16, v244
	v_and_b32_e32 v15, 0xffff0000, v244
	v_lshlrev_b32_e32 v24, 16, v245
	v_and_b32_e32 v25, 0xffff0000, v245
	v_mul_f32_e32 v13, 0xbfb8aa3b, v13
	v_exp_f32_e32 v13, v13
	s_nop 0
	v_add_f32_e32 v13, 1.0, v13
	v_rcp_f32_e32 v14, v13
	v_pk_mul_f32 v[22:23], v[22:23], v[12:13] op_sel_hi:[1,0]
	v_mul_f32_e32 v13, 0xbfb8aa3b, v15
	v_exp_f32_e32 v13, v13
	s_waitcnt vmcnt(0)
	v_pk_mul_f32 v[0:1], v[0:1], v[22:23]
	v_add_f32_e32 v13, 1.0, v13
	v_rcp_f32_e32 v15, v13
	v_mul_f32_e32 v13, 0xbfb8aa3b, v24
	v_exp_f32_e32 v13, v13
	v_pk_mul_f32 v[0:1], v[14:15], v[0:1]
	s_nop 0
	v_cvt_pk_bf16_f32 v0, v0, v1
	v_add_f32_e32 v13, 1.0, v13
	v_rcp_f32_e32 v14, v13
	v_pk_mul_f32 v[20:21], v[20:21], v[12:13] op_sel_hi:[1,0]
	v_mul_f32_e32 v13, 0xbfb8aa3b, v25
	v_exp_f32_e32 v13, v13
	v_pk_mul_f32 v[2:3], v[2:3], v[20:21]
	v_add_f32_e32 v13, 1.0, v13
	v_rcp_f32_e32 v15, v13
	s_nop 0
	v_pk_mul_f32 v[2:3], v[14:15], v[2:3]
	s_nop 0
	v_cvt_pk_bf16_f32 v1, v2, v3
	global_store_dwordx2 v[180:181], v[0:1], off offset:128
	global_load_dwordx2 v[244:245], v[182:183], off offset:160
	global_load_dwordx4 v[0:3], v[64:65], off offset:320
	s_waitcnt vmcnt(0)
	v_lshlrev_b32_e32 v13, 16, v244
	v_and_b32_e32 v15, 0xffff0000, v244
	v_lshlrev_b32_e32 v20, 16, v245
	v_and_b32_e32 v21, 0xffff0000, v245
	v_mul_f32_e32 v13, 0xbfb8aa3b, v13
	v_exp_f32_e32 v13, v13
	s_nop 0
	v_add_f32_e32 v13, 1.0, v13
	v_rcp_f32_e32 v14, v13
	v_pk_mul_f32 v[18:19], v[18:19], v[12:13] op_sel_hi:[1,0]
	v_mul_f32_e32 v13, 0xbfb8aa3b, v15
	v_exp_f32_e32 v13, v13
	s_waitcnt vmcnt(0)
	v_pk_mul_f32 v[0:1], v[0:1], v[18:19]
	v_add_f32_e32 v13, 1.0, v13
	v_rcp_f32_e32 v15, v13
	v_mul_f32_e32 v13, 0xbfb8aa3b, v20
	v_exp_f32_e32 v13, v13
	v_pk_mul_f32 v[0:1], v[14:15], v[0:1]
	s_nop 0
	v_cvt_pk_bf16_f32 v0, v0, v1
	v_add_f32_e32 v13, 1.0, v13
	v_rcp_f32_e32 v14, v13
	v_pk_mul_f32 v[16:17], v[16:17], v[12:13] op_sel_hi:[1,0]
	v_mul_f32_e32 v13, 0xbfb8aa3b, v21
	v_exp_f32_e32 v13, v13
	v_pk_mul_f32 v[2:3], v[2:3], v[16:17]
	v_add_f32_e32 v13, 1.0, v13
	v_rcp_f32_e32 v15, v13
	s_nop 0
	v_pk_mul_f32 v[2:3], v[14:15], v[2:3]
	s_nop 0
	v_cvt_pk_bf16_f32 v1, v2, v3
	global_store_dwordx2 v[180:181], v[0:1], off offset:160
	global_load_dwordx2 v[244:245], v[182:183], off offset:192
	global_load_dwordx4 v[0:3], v[64:65], off offset:384
	s_waitcnt vmcnt(0)
	v_lshlrev_b32_e32 v13, 16, v244
	v_and_b32_e32 v15, 0xffff0000, v244
	v_lshlrev_b32_e32 v16, 16, v245
	v_and_b32_e32 v17, 0xffff0000, v245
	v_mul_f32_e32 v13, 0xbfb8aa3b, v13
	v_exp_f32_e32 v13, v13
	s_nop 0
	v_add_f32_e32 v13, 1.0, v13
	v_pk_mul_f32 v[4:5], v[4:5], v[12:13] op_sel_hi:[1,0]
	v_rcp_f32_e32 v14, v13
	v_pk_mul_f32 v[6:7], v[6:7], v[12:13] op_sel_hi:[1,0]
	s_waitcnt vmcnt(0)
	v_pk_mul_f32 v[0:1], v[0:1], v[4:5]
	v_mul_f32_e32 v4, 0xbfb8aa3b, v15
	v_exp_f32_e32 v4, v4
	v_mul_f32_e32 v5, 0xbfb8aa3b, v17
	v_exp_f32_e32 v5, v5
	v_pk_mul_f32 v[2:3], v[2:3], v[6:7]
	v_add_f32_e32 v4, 1.0, v4
	v_rcp_f32_e32 v15, v4
	v_mul_f32_e32 v4, 0xbfb8aa3b, v16
	v_exp_f32_e32 v4, v4
	v_add_f32_e32 v5, 1.0, v5
	v_rcp_f32_e32 v5, v5
	v_pk_mul_f32 v[0:1], v[14:15], v[0:1]
	v_add_f32_e32 v4, 1.0, v4
	v_rcp_f32_e32 v4, v4
	v_cvt_pk_bf16_f32 v0, v0, v1
	v_pk_mul_f32 v[2:3], v[4:5], v[2:3]
	s_nop 0
	v_cvt_pk_bf16_f32 v1, v2, v3
	global_store_dwordx2 v[180:181], v[0:1], off offset:192
	global_load_dwordx2 v[244:245], v[182:183], off offset:224
	global_load_dwordx4 v[0:3], v[64:65], off offset:448
	s_waitcnt vmcnt(0)
	v_lshlrev_b32_e32 v4, 16, v244
	v_and_b32_e32 v5, 0xffff0000, v244
	v_lshlrev_b32_e32 v13, 16, v245
	v_and_b32_e32 v14, 0xffff0000, v245
	v_mul_f32_e32 v4, 0xbfb8aa3b, v4
	v_mul_f32_e32 v5, 0xbfb8aa3b, v5
	v_exp_f32_e32 v4, v4
	v_exp_f32_e32 v5, v5
	v_pk_mul_f32 v[6:7], v[10:11], v[12:13] op_sel_hi:[1,0]
	v_add_f32_e32 v4, 1.0, v4
	v_add_f32_e32 v5, 1.0, v5
	v_rcp_f32_e32 v4, v4
	v_rcp_f32_e32 v5, v5
	s_waitcnt vmcnt(0)
	v_pk_mul_f32 v[0:1], v[0:1], v[6:7]
	s_nop 0
	v_pk_mul_f32 v[0:1], v[4:5], v[0:1]
	v_mul_f32_e32 v4, 0xbfb8aa3b, v13
	v_mul_f32_e32 v5, 0xbfb8aa3b, v14
	v_exp_f32_e32 v4, v4
	v_exp_f32_e32 v5, v5
	v_pk_mul_f32 v[6:7], v[8:9], v[12:13] op_sel_hi:[1,0]
	v_cvt_pk_bf16_f32 v0, v0, v1
	v_add_f32_e32 v4, 1.0, v4
	v_add_f32_e32 v5, 1.0, v5
	v_rcp_f32_e32 v4, v4
	v_rcp_f32_e32 v5, v5
	v_pk_mul_f32 v[2:3], v[2:3], v[6:7]
	s_nop 0
	v_pk_mul_f32 v[2:3], v[4:5], v[2:3]
	s_nop 0
	v_cvt_pk_bf16_f32 v1, v2, v3
	global_store_dwordx2 v[180:181], v[0:1], off offset:224
	s_cbranch_vccz .LBB0_506
	s_add_i32 s84, s84, s96
	s_cmpk_gt_i32 s84, 0x3ff
	s_cbranch_scc0 .LBB0_501
